# static s_setprio 1 for waves 4-7 at kernel entry; per-segment setprio flips in the attention tile loop deleted
# baseline (speedup 1.0000x reference)
; #define LAS __attribute__((address_space(3)))
; __global__ void __launch_bounds__(512) fwd_megakernel(Params p) {
;   __shared__ __attribute__((aligned(1024))) char smem[155648];
;   cg::grid_group grid = cg::this_grid();
;   const int G = gridDim.x;
;   char* ws = p.ws;
;   unsigned* bar = (unsigned*)(ws + OFF_BAR);
;   volatile LAS unsigned* xst = (volatile LAS unsigned*)(smem + 155648 - 16);
;   if (threadIdx.x == 0) { xst[0] = 0u; xst[1] = 0u; }
;   const XcdBarrier xb = xcd_barrier_post(bar, xst);
_Z14fwd_megakernel6Params:
	s_load_dword s78, s[0:1], 0xc8
	s_load_dwordx2 s[96:97], s[0:1], 0xc0
	s_add_u32 s6, s0, 0xc8
	s_addc_u32 s7, s1, 0
	v_mov_b32_e32 v1, 0
	v_readfirstlane_b32 s10, v0
	s_nop 3
	s_and_b32 s10, s10, 0x3ff
	s_lshr_b32 s10, s10, 6
	s_cmp_ge_u32 s10, 4
	s_cbranch_scc0 .Lprio_done
	s_setprio 1
.Lprio_done:
	s_waitcnt lgkmcnt(0)
	s_cmp_lt_u32 s2, s78
	s_cselect_b32 s3, 12, 18
	s_add_u32 s4, s6, s3
	s_addc_u32 s5, s7, 0
	global_load_ushort v2, v1, s[4:5]
	v_and_b32_e32 v166, 0x3ff, v0
	v_cmp_eq_u32_e64 s[8:9], 0, v166
	s_waitcnt vmcnt(0)
	v_readfirstlane_b32 s3, v2
	s_mov_b64 s[4:5], exec
	v_writelane_b32 v255, s8, 0
	s_nop 1
	v_writelane_b32 v255, s9, 1
	s_and_b64 s[8:9], s[4:5], s[8:9]
	s_mov_b64 exec, s[8:9]
	s_cbranch_execz .LBB0_2
	v_mov_b32_e32 v2, 0x25ff0
	ds_write_b32 v2, v1
	v_mov_b32_e32 v2, 0x25ff4
	ds_write_b32 v2, v1

; #define MFMA(a, b, c) __builtin_amdgcn_mfma_f32_32x32x16_bf16((a), (b), (c), 0, 0, 0)
; DI f32x16 zero16() { f32x16 z; for (int i = 0; i < 16; ++i) z[i] = 0.f; return z; }
; DI void dsa_attn_item(const Params& p, int b, int qblk, char* smem) {
;     ...
;     for (int t8 = 0; t8 < 8; ++t8) {
;       const int g = c * 8 + t8;
;       if (g > qblk) break;
;       {
;         const int gn = min(g + 1, qblk);
;         const u16* kr = kfr + (size_t)gn * 2048;
; #pragma unroll
;         for (int ks = 0; ks < 4; ++ks) Kn[ks] = ldg8(kr + ks * 512);
; #pragma unroll
;         for (int dt = 0; dt < 2; ++dt)
; #pragma unroll
;           for (int s = 0; s < 2; ++s) Vn[dt][s] = ldg8(vfr + (size_t)gn * 2048 + (dt * 2 + s) * 512);
;       }
;       const unsigned bits = maskbuf[(buf * 8 + t8) * 64 + lane];
;       f32x16 Sx = zero16();
;       __builtin_amdgcn_s_setprio(1);
; #pragma unroll
;       for (int ks = 0; ks < 4; ++ks) Sx = MFMA(Kf[ks], Qf[ks], Sx);
;       __builtin_amdgcn_s_setprio(0);
.Lattn_hdrA:
	s_add_i32 s7, s53, s6
	s_cmp_le_u32 s7, s52
	s_cselect_b64 s[0:1], -1, 0
	s_cmp_gt_u32 s7, s52
	s_cbranch_scc1 .LBB0_446
	s_add_i32 s60, s7, 2
	s_min_i32 s40, s60, s52
	s_lshl_b64 s[10:11], s[40:41], 12
	s_waitcnt vmcnt(12) lgkmcnt(0)
	v_mfma_f32_32x32x16_bf16 v[34:49], v[150:153], v[98:101], v[238:253]
	v_mfma_f32_32x32x16_bf16 v[34:49], v[146:149], v[102:105], v[34:49]
	v_mfma_f32_32x32x16_bf16 v[34:49], v[142:145], v[106:109], v[34:49]
	v_mfma_f32_32x32x16_bf16 v[34:49], v[138:141], v[110:113], v[34:49]
	s_cmp_lt_u32 s6, 7
	s_cbranch_scc0 .Lattn_nokA
	v_add_u32_e32 v0, 0x1000, v0
	v_lshl_add_u64 v[160:161], v[198:199], 0, s[10:11]
	ds_read_b128 v[238:241], v0
	ds_read_b128 v[242:245], v0 offset:1024
	ds_read_b128 v[246:249], v0 offset:2048
	ds_read_b128 v[250:253], v0 offset:3072
	global_load_dwordx4 v[150:153], v[160:161], off
	global_load_dwordx4 v[146:149], v[160:161], off offset:1024
	global_load_dwordx4 v[142:145], v[160:161], off offset:2048
	global_load_dwordx4 v[138:141], v[160:161], off offset:3072

; #define MFMA(a, b, c) __builtin_amdgcn_mfma_f32_32x32x16_bf16((a), (b), (c), 0, 0, 0)
; DI void dsa_attn_item(const Params& p, int b, int qblk, char* smem) {
;     ...
;       const float msafe = (mrun == -INFINITY) ? 0.f : mrun;
;       float pv[16]; float ps = 0.f;
; #pragma unroll
;       for (int i = 0; i < 16; ++i) { pv[i] = __builtin_amdgcn_exp2f(sm[i] - msafe); ps += pv[i]; }
;       lrun += ps;
;       bf16x8 Pf[2];
; #pragma unroll
;       for (int s = 0; s < 2; ++s) Pf[s] = pack8(pv[8 * s], pv[8 * s + 1], pv[8 * s + 2], pv[8 * s + 3], pv[8 * s + 4], pv[8 * s + 5], pv[8 * s + 6], pv[8 * s + 7]);
;       __builtin_amdgcn_s_setprio(1);
; #pragma unroll
;       for (int dt = 0; dt < 2; ++dt)
; #pragma unroll
;         for (int s = 0; s < 2; ++s) O[dt] = MFMA(Vf[dt][s], Pf[s], O[dt]);
;       __builtin_amdgcn_s_setprio(0);
; #pragma unroll
;       for (int ks = 0; ks < 4; ++ks) Kf[ks] = Kn[ks];
; #pragma unroll
;       for (int dt = 0; dt < 2; ++dt)
; #pragma unroll
;         for (int s = 0; s < 2; ++s) Vf[dt][s] = Vn[dt][s];
.Lattn_442A:
	v_pk_add_f32 v[34:35], v[34:35], v[162:163] op_sel_hi:[1,0] neg_lo:[0,1] neg_hi:[0,1]
	v_pk_add_f32 v[36:37], v[36:37], v[162:163] op_sel_hi:[1,0] neg_lo:[0,1] neg_hi:[0,1]
	v_pk_add_f32 v[38:39], v[38:39], v[162:163] op_sel_hi:[1,0] neg_lo:[0,1] neg_hi:[0,1]
	v_pk_add_f32 v[40:41], v[40:41], v[162:163] op_sel_hi:[1,0] neg_lo:[0,1] neg_hi:[0,1]
	v_pk_add_f32 v[42:43], v[42:43], v[162:163] op_sel_hi:[1,0] neg_lo:[0,1] neg_hi:[0,1]
	v_pk_add_f32 v[44:45], v[44:45], v[162:163] op_sel_hi:[1,0] neg_lo:[0,1] neg_hi:[0,1]
	v_pk_add_f32 v[46:47], v[46:47], v[162:163] op_sel_hi:[1,0] neg_lo:[0,1] neg_hi:[0,1]
	v_pk_add_f32 v[48:49], v[48:49], v[162:163] op_sel_hi:[1,0] neg_lo:[0,1] neg_hi:[0,1]
	v_exp_f32_e32 v34, v34
	v_exp_f32_e32 v35, v35
	v_exp_f32_e32 v36, v36
	v_exp_f32_e32 v37, v37
	v_exp_f32_e32 v38, v38
	v_exp_f32_e32 v39, v39
	v_exp_f32_e32 v40, v40
	v_exp_f32_e32 v41, v41
	v_exp_f32_e32 v42, v42
	v_exp_f32_e32 v43, v43
	v_exp_f32_e32 v44, v44
	v_exp_f32_e32 v45, v45
	v_exp_f32_e32 v46, v46
	v_exp_f32_e32 v47, v47
	v_exp_f32_e32 v48, v48
	v_exp_f32_e32 v49, v49
	v_pk_add_f32 v[154:155], v[34:35], v[36:37]
	v_pk_add_f32 v[156:157], v[38:39], v[40:41]
	v_pk_add_f32 v[158:159], v[42:43], v[44:45]
	v_pk_add_f32 v[160:161], v[46:47], v[48:49]
	v_cvt_pk_bf16_f32 v34, v34, v35
	v_cvt_pk_bf16_f32 v35, v36, v37
	v_cvt_pk_bf16_f32 v36, v38, v39
	v_cvt_pk_bf16_f32 v37, v40, v41
	v_cvt_pk_bf16_f32 v38, v42, v43
	v_cvt_pk_bf16_f32 v39, v44, v45
	v_cvt_pk_bf16_f32 v40, v46, v47
	v_cvt_pk_bf16_f32 v41, v48, v49
	v_pk_add_f32 v[154:155], v[154:155], v[156:157]
	v_pk_add_f32 v[158:159], v[158:159], v[160:161]
	s_nop 0
	v_pk_add_f32 v[154:155], v[154:155], v[158:159]
	s_nop 0
	v_add_f32_e32 v154, v154, v155
	s_waitcnt vmcnt(8)
	v_add_f32_e32 v171, v171, v154
	v_mfma_f32_32x32x16_bf16 v[18:33], v[126:129], v[34:37], v[18:33]
	v_mfma_f32_32x32x16_bf16 v[2:17], v[118:121], v[34:37], v[2:17]
	v_mfma_f32_32x32x16_bf16 v[18:33], v[122:125], v[38:41], v[18:33]
	v_mfma_f32_32x32x16_bf16 v[2:17], v[114:117], v[38:41], v[2:17]
	s_cmp_lt_u32 s6, 7
	s_cbranch_scc0 .Lattn_novA
	v_lshl_add_u64 v[160:161], v[200:201], 0, s[10:11]
	global_load_dwordx4 v[126:129], v[160:161], off
	global_load_dwordx4 v[122:125], v[160:161], off offset:1024
	global_load_dwordx4 v[118:121], v[160:161], off offset:2048
	global_load_dwordx4 v[114:117], v[160:161], off offset:3072

; #define MFMA(a, b, c) __builtin_amdgcn_mfma_f32_32x32x16_bf16((a), (b), (c), 0, 0, 0)
; DI f32x16 zero16() { f32x16 z; for (int i = 0; i < 16; ++i) z[i] = 0.f; return z; }
; DI void dsa_attn_item(const Params& p, int b, int qblk, char* smem) {
;     ...
;     for (int t8 = 0; t8 < 8; ++t8) {
;       const int g = c * 8 + t8;
;       if (g > qblk) break;
;       {
;         const int gn = min(g + 1, qblk);
;         const u16* kr = kfr + (size_t)gn * 2048;
; #pragma unroll
;         for (int ks = 0; ks < 4; ++ks) Kn[ks] = ldg8(kr + ks * 512);
; #pragma unroll
;         for (int dt = 0; dt < 2; ++dt)
; #pragma unroll
;           for (int s = 0; s < 2; ++s) Vn[dt][s] = ldg8(vfr + (size_t)gn * 2048 + (dt * 2 + s) * 512);
;       }
;       const unsigned bits = maskbuf[(buf * 8 + t8) * 64 + lane];
;       f32x16 Sx = zero16();
;       __builtin_amdgcn_s_setprio(1);
; #pragma unroll
;       for (int ks = 0; ks < 4; ++ks) Sx = MFMA(Kf[ks], Qf[ks], Sx);
;       __builtin_amdgcn_s_setprio(0);
.Lattn_hdrB:
	s_add_i32 s7, s53, s6
	s_cmp_le_u32 s7, s52
	s_cselect_b64 s[0:1], -1, 0
	s_cmp_gt_u32 s7, s52
	s_cbranch_scc1 .LBB0_446
	s_add_i32 s60, s7, 2
	s_min_i32 s40, s60, s52
	s_lshl_b64 s[10:11], s[40:41], 12
	s_waitcnt vmcnt(12) lgkmcnt(0)
	v_mfma_f32_32x32x16_bf16 v[34:49], v[66:69], v[98:101], v[238:253]
	v_mfma_f32_32x32x16_bf16 v[34:49], v[70:73], v[102:105], v[34:49]
	v_mfma_f32_32x32x16_bf16 v[34:49], v[74:77], v[106:109], v[34:49]
	v_mfma_f32_32x32x16_bf16 v[34:49], v[78:81], v[110:113], v[34:49]
	s_cmp_lt_u32 s6, 7
	s_cbranch_scc0 .Lattn_nokB
	v_add_u32_e32 v0, 0x1000, v0
	v_lshl_add_u64 v[160:161], v[198:199], 0, s[10:11]
	ds_read_b128 v[238:241], v0
	ds_read_b128 v[242:245], v0 offset:1024
	ds_read_b128 v[246:249], v0 offset:2048
	ds_read_b128 v[250:253], v0 offset:3072
	global_load_dwordx4 v[66:69], v[160:161], off
	global_load_dwordx4 v[70:73], v[160:161], off offset:1024
	global_load_dwordx4 v[74:77], v[160:161], off offset:2048
	global_load_dwordx4 v[78:81], v[160:161], off offset:3072

; #define MFMA(a, b, c) __builtin_amdgcn_mfma_f32_32x32x16_bf16((a), (b), (c), 0, 0, 0)
; DI void dsa_attn_item(const Params& p, int b, int qblk, char* smem) {
;     ...
;       const float msafe = (mrun == -INFINITY) ? 0.f : mrun;
;       float pv[16]; float ps = 0.f;
; #pragma unroll
;       for (int i = 0; i < 16; ++i) { pv[i] = __builtin_amdgcn_exp2f(sm[i] - msafe); ps += pv[i]; }
;       lrun += ps;
;       bf16x8 Pf[2];
; #pragma unroll
;       for (int s = 0; s < 2; ++s) Pf[s] = pack8(pv[8 * s], pv[8 * s + 1], pv[8 * s + 2], pv[8 * s + 3], pv[8 * s + 4], pv[8 * s + 5], pv[8 * s + 6], pv[8 * s + 7]);
;       __builtin_amdgcn_s_setprio(1);
; #pragma unroll
;       for (int dt = 0; dt < 2; ++dt)
; #pragma unroll
;         for (int s = 0; s < 2; ++s) O[dt] = MFMA(Vf[dt][s], Pf[s], O[dt]);
;       __builtin_amdgcn_s_setprio(0);
; #pragma unroll
;       for (int ks = 0; ks < 4; ++ks) Kf[ks] = Kn[ks];
; #pragma unroll
;       for (int dt = 0; dt < 2; ++dt)
; #pragma unroll
;         for (int s = 0; s < 2; ++s) Vf[dt][s] = Vn[dt][s];
.Lattn_442B:
	v_pk_add_f32 v[34:35], v[34:35], v[162:163] op_sel_hi:[1,0] neg_lo:[0,1] neg_hi:[0,1]
	v_pk_add_f32 v[36:37], v[36:37], v[162:163] op_sel_hi:[1,0] neg_lo:[0,1] neg_hi:[0,1]
	v_pk_add_f32 v[38:39], v[38:39], v[162:163] op_sel_hi:[1,0] neg_lo:[0,1] neg_hi:[0,1]
	v_pk_add_f32 v[40:41], v[40:41], v[162:163] op_sel_hi:[1,0] neg_lo:[0,1] neg_hi:[0,1]
	v_pk_add_f32 v[42:43], v[42:43], v[162:163] op_sel_hi:[1,0] neg_lo:[0,1] neg_hi:[0,1]
	v_pk_add_f32 v[44:45], v[44:45], v[162:163] op_sel_hi:[1,0] neg_lo:[0,1] neg_hi:[0,1]
	v_pk_add_f32 v[46:47], v[46:47], v[162:163] op_sel_hi:[1,0] neg_lo:[0,1] neg_hi:[0,1]
	v_pk_add_f32 v[48:49], v[48:49], v[162:163] op_sel_hi:[1,0] neg_lo:[0,1] neg_hi:[0,1]
	v_exp_f32_e32 v34, v34
	v_exp_f32_e32 v35, v35
	v_exp_f32_e32 v36, v36
	v_exp_f32_e32 v37, v37
	v_exp_f32_e32 v38, v38
	v_exp_f32_e32 v39, v39
	v_exp_f32_e32 v40, v40
	v_exp_f32_e32 v41, v41
	v_exp_f32_e32 v42, v42
	v_exp_f32_e32 v43, v43
	v_exp_f32_e32 v44, v44
	v_exp_f32_e32 v45, v45
	v_exp_f32_e32 v46, v46
	v_exp_f32_e32 v47, v47
	v_exp_f32_e32 v48, v48
	v_exp_f32_e32 v49, v49
	v_pk_add_f32 v[154:155], v[34:35], v[36:37]
	v_pk_add_f32 v[156:157], v[38:39], v[40:41]
	v_pk_add_f32 v[158:159], v[42:43], v[44:45]
	v_pk_add_f32 v[160:161], v[46:47], v[48:49]
	v_cvt_pk_bf16_f32 v34, v34, v35
	v_cvt_pk_bf16_f32 v35, v36, v37
	v_cvt_pk_bf16_f32 v36, v38, v39
	v_cvt_pk_bf16_f32 v37, v40, v41
	v_cvt_pk_bf16_f32 v38, v42, v43
	v_cvt_pk_bf16_f32 v39, v44, v45
	v_cvt_pk_bf16_f32 v40, v46, v47
	v_cvt_pk_bf16_f32 v41, v48, v49
	v_pk_add_f32 v[154:155], v[154:155], v[156:157]
	v_pk_add_f32 v[158:159], v[158:159], v[160:161]
	s_nop 0
	v_pk_add_f32 v[154:155], v[154:155], v[158:159]
	s_nop 0
	v_add_f32_e32 v154, v154, v155
	s_waitcnt vmcnt(8)
	v_add_f32_e32 v171, v171, v154
	v_mfma_f32_32x32x16_bf16 v[18:33], v[50:53], v[34:37], v[18:33]
	v_mfma_f32_32x32x16_bf16 v[2:17], v[58:61], v[34:37], v[2:17]
	v_mfma_f32_32x32x16_bf16 v[18:33], v[54:57], v[38:41], v[18:33]
	v_mfma_f32_32x32x16_bf16 v[2:17], v[62:65], v[38:41], v[2:17]
	s_cmp_lt_u32 s6, 7
	s_cbranch_scc0 .Lattn_novB
	v_lshl_add_u64 v[160:161], v[200:201], 0, s[10:11]
	global_load_dwordx4 v[50:53], v[160:161], off
	global_load_dwordx4 v[54:57], v[160:161], off offset:1024
	global_load_dwordx4 v[58:61], v[160:161], off offset:2048
	global_load_dwordx4 v[62:65], v[160:161], off offset:3072
